# P0 wcsT item: all 64 loads issued up front, 8 unrolled trig/fma groups with counted waits
# baseline (speedup 1.0000x reference)
.LBB0_48:
	s_andn2_b64 vcc, exec, s[2:3]
	s_cbranch_vccnz .LBB0_52
	s_lshl_b32 s2, s14, 8
	s_add_i32 s2, s2, 0xfffd0000
	v_add_u32_e32 v4, s2, v2
	s_load_dwordx16 s[16:31], s[0:1], 0x80
	v_ashrrev_i32_e32 v6, 13, v4
	v_ashrrev_i32_e32 v7, 31, v6
	v_add_u32_e32 v8, s8, v2
	v_lshlrev_b64 v[6:7], 14, v[6:7]
	v_lshrrev_b32_e32 v8, 4, v8
	s_movk_i32 s2, 0xfc
	v_and_b32_e32 v3, 0x1000, v4
	v_and_or_b32 v6, v8, s2, v6
	v_mov_b32_e32 v0, 0
	v_cmp_eq_u32_e32 vcc, 0, v3
	v_lshlrev_b32_e32 v3, 3, v2
	v_mul_lo_u32 v5, v2, 7
	v_mul_lo_u32 v12, v2, 6
	v_lshl_add_u32 v13, v2, 2, v2
	v_lshlrev_b32_e32 v14, 2, v2
	v_lshl_add_u32 v15, v2, 1, v2
	v_lshlrev_b32_e32 v16, 1, v2
	s_waitcnt lgkmcnt(0)
	v_lshl_add_u64 v[6:7], s[26:27], 0, v[6:7]
	s_mov_b64 s[2:3], 0
	v_mov_b32_e32 v17, 0
	v_lshl_add_u64 v[8:9], v[6:7], 0, s[2:3]
	global_load_dword v140, v[8:9], off
	global_load_dword v141, v[8:9], off offset:256
	global_load_dword v142, v[8:9], off offset:512
	global_load_dword v143, v[8:9], off offset:768
	global_load_dword v144, v[8:9], off offset:1024
	global_load_dword v145, v[8:9], off offset:1280
	global_load_dword v146, v[8:9], off offset:1536
	global_load_dword v147, v[8:9], off offset:1792
	s_add_u32 s2, s2, 0x800
	s_addc_u32 s3, s3, 0
	v_lshl_add_u64 v[8:9], v[6:7], 0, s[2:3]
	global_load_dword v148, v[8:9], off
	global_load_dword v149, v[8:9], off offset:256
	global_load_dword v150, v[8:9], off offset:512
	global_load_dword v151, v[8:9], off offset:768
	global_load_dword v152, v[8:9], off offset:1024
	global_load_dword v153, v[8:9], off offset:1280
	global_load_dword v154, v[8:9], off offset:1536
	global_load_dword v155, v[8:9], off offset:1792
	s_add_u32 s2, s2, 0x800
	s_addc_u32 s3, s3, 0
	v_lshl_add_u64 v[8:9], v[6:7], 0, s[2:3]
	global_load_dword v156, v[8:9], off
	global_load_dword v157, v[8:9], off offset:256
	global_load_dword v158, v[8:9], off offset:512
	global_load_dword v159, v[8:9], off offset:768
	global_load_dword v160, v[8:9], off offset:1024
	global_load_dword v161, v[8:9], off offset:1280
	global_load_dword v162, v[8:9], off offset:1536
	global_load_dword v163, v[8:9], off offset:1792
	s_add_u32 s2, s2, 0x800
	s_addc_u32 s3, s3, 0
	v_lshl_add_u64 v[8:9], v[6:7], 0, s[2:3]
	global_load_dword v164, v[8:9], off
	global_load_dword v165, v[8:9], off offset:256
	global_load_dword v166, v[8:9], off offset:512
	global_load_dword v167, v[8:9], off offset:768
	global_load_dword v168, v[8:9], off offset:1024
	global_load_dword v169, v[8:9], off offset:1280
	global_load_dword v170, v[8:9], off offset:1536
	global_load_dword v171, v[8:9], off offset:1792
	s_add_u32 s2, s2, 0x800
	s_addc_u32 s3, s3, 0
	v_lshl_add_u64 v[8:9], v[6:7], 0, s[2:3]
	global_load_dword v172, v[8:9], off
	global_load_dword v173, v[8:9], off offset:256
	global_load_dword v174, v[8:9], off offset:512
	global_load_dword v175, v[8:9], off offset:768
	global_load_dword v176, v[8:9], off offset:1024
	global_load_dword v177, v[8:9], off offset:1280
	global_load_dword v178, v[8:9], off offset:1536
	global_load_dword v179, v[8:9], off offset:1792
	s_add_u32 s2, s2, 0x800
	s_addc_u32 s3, s3, 0
	v_lshl_add_u64 v[8:9], v[6:7], 0, s[2:3]
	global_load_dword v180, v[8:9], off
	global_load_dword v181, v[8:9], off offset:256
	global_load_dword v182, v[8:9], off offset:512
	global_load_dword v183, v[8:9], off offset:768
	global_load_dword v184, v[8:9], off offset:1024
	global_load_dword v185, v[8:9], off offset:1280
	global_load_dword v186, v[8:9], off offset:1536
	global_load_dword v187, v[8:9], off offset:1792
	s_add_u32 s2, s2, 0x800
	s_addc_u32 s3, s3, 0
	v_lshl_add_u64 v[8:9], v[6:7], 0, s[2:3]
	global_load_dword v188, v[8:9], off
	global_load_dword v189, v[8:9], off offset:256
	global_load_dword v190, v[8:9], off offset:512
	global_load_dword v191, v[8:9], off offset:768
	global_load_dword v192, v[8:9], off offset:1024
	global_load_dword v193, v[8:9], off offset:1280
	global_load_dword v194, v[8:9], off offset:1536
	global_load_dword v195, v[8:9], off offset:1792
	s_add_u32 s2, s2, 0x800
	s_addc_u32 s3, s3, 0
	v_lshl_add_u64 v[8:9], v[6:7], 0, s[2:3]
	global_load_dword v196, v[8:9], off
	global_load_dword v197, v[8:9], off offset:256
	global_load_dword v198, v[8:9], off offset:512
	global_load_dword v199, v[8:9], off offset:768
	global_load_dword v200, v[8:9], off offset:1024
	global_load_dword v201, v[8:9], off offset:1280
	global_load_dword v202, v[8:9], off offset:1536
	global_load_dword v203, v[8:9], off offset:1792
	s_add_u32 s2, s2, 0x800
	s_addc_u32 s3, s3, 0
	v_and_b32_e32 v18, 56, v0
	v_cvt_f32_ubyte0_e32 v18, v18
	v_mul_f32_e32 v18, 0x3c800000, v18
	v_sin_f32_e32 v19, v18
	v_cos_f32_e32 v18, v18
	s_nop 0
	v_cndmask_b32_e32 v118, v19, v18, vcc
	v_add_u32_e32 v18, v2, v0
	v_and_b32_e32 v18, 63, v18
	v_cvt_f32_ubyte0_e32 v18, v18
	v_mul_f32_e32 v18, 0x3c800000, v18
	v_sin_f32_e32 v19, v18
	v_cos_f32_e32 v18, v18
	s_nop 0
	v_cndmask_b32_e32 v119, v19, v18, vcc
	v_add_u32_e32 v18, v16, v0
	v_and_b32_e32 v18, 62, v18
	v_cvt_f32_ubyte0_e32 v18, v18
	v_mul_f32_e32 v18, 0x3c800000, v18
	v_sin_f32_e32 v19, v18
	v_cos_f32_e32 v18, v18
	s_nop 0
	v_cndmask_b32_e32 v120, v19, v18, vcc
	v_add_u32_e32 v18, v15, v0
	v_and_b32_e32 v18, 63, v18
	v_cvt_f32_ubyte0_e32 v18, v18
	v_mul_f32_e32 v18, 0x3c800000, v18
	v_sin_f32_e32 v19, v18
	v_cos_f32_e32 v18, v18
	s_nop 0
	v_cndmask_b32_e32 v121, v19, v18, vcc
	v_add_u32_e32 v18, v14, v0
	v_and_b32_e32 v18, 60, v18
	v_cvt_f32_ubyte0_e32 v18, v18
	v_mul_f32_e32 v18, 0x3c800000, v18
	v_sin_f32_e32 v19, v18
	v_cos_f32_e32 v18, v18
	s_nop 0
	v_cndmask_b32_e32 v122, v19, v18, vcc
	v_add_u32_e32 v18, v13, v0
	v_and_b32_e32 v18, 63, v18
	v_cvt_f32_ubyte0_e32 v18, v18
	v_mul_f32_e32 v18, 0x3c800000, v18
	v_sin_f32_e32 v19, v18
	v_cos_f32_e32 v18, v18
	s_nop 0
	v_cndmask_b32_e32 v123, v19, v18, vcc
	v_add_u32_e32 v18, v12, v0
	v_and_b32_e32 v18, 62, v18
	v_cvt_f32_ubyte0_e32 v18, v18
	v_mul_f32_e32 v18, 0x3c800000, v18
	v_sin_f32_e32 v19, v18
	v_cos_f32_e32 v18, v18
	s_nop 0
	v_cndmask_b32_e32 v124, v19, v18, vcc
	v_add_u32_e32 v18, v5, v0
	v_and_b32_e32 v18, 63, v18
	v_cvt_f32_ubyte0_e32 v18, v18
	v_mul_f32_e32 v18, 0x3c800000, v18
	v_sin_f32_e32 v19, v18
	v_cos_f32_e32 v18, v18
	s_nop 0
	v_cndmask_b32_e32 v125, v19, v18, vcc
	v_add_u32_e32 v0, v0, v3
	s_waitcnt vmcnt(56)
	v_fmac_f32_e32 v17, v140, v118
	v_fmac_f32_e32 v17, v141, v119
	v_fmac_f32_e32 v17, v142, v120
	v_fmac_f32_e32 v17, v143, v121
	v_fmac_f32_e32 v17, v144, v122
	v_fmac_f32_e32 v17, v145, v123
	v_fmac_f32_e32 v17, v146, v124
	v_fmac_f32_e32 v17, v147, v125
	v_and_b32_e32 v18, 56, v0
	v_cvt_f32_ubyte0_e32 v18, v18
	v_mul_f32_e32 v18, 0x3c800000, v18
	v_sin_f32_e32 v19, v18
	v_cos_f32_e32 v18, v18
	s_nop 0
	v_cndmask_b32_e32 v118, v19, v18, vcc
	v_add_u32_e32 v18, v2, v0
	v_and_b32_e32 v18, 63, v18
	v_cvt_f32_ubyte0_e32 v18, v18
	v_mul_f32_e32 v18, 0x3c800000, v18
	v_sin_f32_e32 v19, v18
	v_cos_f32_e32 v18, v18
	s_nop 0
	v_cndmask_b32_e32 v119, v19, v18, vcc
	v_add_u32_e32 v18, v16, v0
	v_and_b32_e32 v18, 62, v18
	v_cvt_f32_ubyte0_e32 v18, v18
	v_mul_f32_e32 v18, 0x3c800000, v18
	v_sin_f32_e32 v19, v18
	v_cos_f32_e32 v18, v18
	s_nop 0
	v_cndmask_b32_e32 v120, v19, v18, vcc
	v_add_u32_e32 v18, v15, v0
	v_and_b32_e32 v18, 63, v18
	v_cvt_f32_ubyte0_e32 v18, v18
	v_mul_f32_e32 v18, 0x3c800000, v18
	v_sin_f32_e32 v19, v18
	v_cos_f32_e32 v18, v18
	s_nop 0
	v_cndmask_b32_e32 v121, v19, v18, vcc
	v_add_u32_e32 v18, v14, v0
	v_and_b32_e32 v18, 60, v18
	v_cvt_f32_ubyte0_e32 v18, v18
	v_mul_f32_e32 v18, 0x3c800000, v18
	v_sin_f32_e32 v19, v18
	v_cos_f32_e32 v18, v18
	s_nop 0
	v_cndmask_b32_e32 v122, v19, v18, vcc
	v_add_u32_e32 v18, v13, v0
	v_and_b32_e32 v18, 63, v18
	v_cvt_f32_ubyte0_e32 v18, v18
	v_mul_f32_e32 v18, 0x3c800000, v18
	v_sin_f32_e32 v19, v18
	v_cos_f32_e32 v18, v18
	s_nop 0
	v_cndmask_b32_e32 v123, v19, v18, vcc
	v_add_u32_e32 v18, v12, v0
	v_and_b32_e32 v18, 62, v18
	v_cvt_f32_ubyte0_e32 v18, v18
	v_mul_f32_e32 v18, 0x3c800000, v18
	v_sin_f32_e32 v19, v18
	v_cos_f32_e32 v18, v18
	s_nop 0
	v_cndmask_b32_e32 v124, v19, v18, vcc
	v_add_u32_e32 v18, v5, v0
	v_and_b32_e32 v18, 63, v18
	v_cvt_f32_ubyte0_e32 v18, v18
	v_mul_f32_e32 v18, 0x3c800000, v18
	v_sin_f32_e32 v19, v18
	v_cos_f32_e32 v18, v18
	s_nop 0
	v_cndmask_b32_e32 v125, v19, v18, vcc
	v_add_u32_e32 v0, v0, v3
	s_waitcnt vmcnt(48)
	v_fmac_f32_e32 v17, v148, v118
	v_fmac_f32_e32 v17, v149, v119
	v_fmac_f32_e32 v17, v150, v120
	v_fmac_f32_e32 v17, v151, v121
	v_fmac_f32_e32 v17, v152, v122
	v_fmac_f32_e32 v17, v153, v123
	v_fmac_f32_e32 v17, v154, v124
	v_fmac_f32_e32 v17, v155, v125
	v_and_b32_e32 v18, 56, v0
	v_cvt_f32_ubyte0_e32 v18, v18
	v_mul_f32_e32 v18, 0x3c800000, v18
	v_sin_f32_e32 v19, v18
	v_cos_f32_e32 v18, v18
	s_nop 0
	v_cndmask_b32_e32 v118, v19, v18, vcc
	v_add_u32_e32 v18, v2, v0
	v_and_b32_e32 v18, 63, v18
	v_cvt_f32_ubyte0_e32 v18, v18
	v_mul_f32_e32 v18, 0x3c800000, v18
	v_sin_f32_e32 v19, v18
	v_cos_f32_e32 v18, v18
	s_nop 0
	v_cndmask_b32_e32 v119, v19, v18, vcc
	v_add_u32_e32 v18, v16, v0
	v_and_b32_e32 v18, 62, v18
	v_cvt_f32_ubyte0_e32 v18, v18
	v_mul_f32_e32 v18, 0x3c800000, v18
	v_sin_f32_e32 v19, v18
	v_cos_f32_e32 v18, v18
	s_nop 0
	v_cndmask_b32_e32 v120, v19, v18, vcc
	v_add_u32_e32 v18, v15, v0
	v_and_b32_e32 v18, 63, v18
	v_cvt_f32_ubyte0_e32 v18, v18
	v_mul_f32_e32 v18, 0x3c800000, v18
	v_sin_f32_e32 v19, v18
	v_cos_f32_e32 v18, v18
	s_nop 0
	v_cndmask_b32_e32 v121, v19, v18, vcc
	v_add_u32_e32 v18, v14, v0
	v_and_b32_e32 v18, 60, v18
	v_cvt_f32_ubyte0_e32 v18, v18
	v_mul_f32_e32 v18, 0x3c800000, v18
	v_sin_f32_e32 v19, v18
	v_cos_f32_e32 v18, v18
	s_nop 0
	v_cndmask_b32_e32 v122, v19, v18, vcc
	v_add_u32_e32 v18, v13, v0
	v_and_b32_e32 v18, 63, v18
	v_cvt_f32_ubyte0_e32 v18, v18
	v_mul_f32_e32 v18, 0x3c800000, v18
	v_sin_f32_e32 v19, v18
	v_cos_f32_e32 v18, v18
	s_nop 0
	v_cndmask_b32_e32 v123, v19, v18, vcc
	v_add_u32_e32 v18, v12, v0
	v_and_b32_e32 v18, 62, v18
	v_cvt_f32_ubyte0_e32 v18, v18
	v_mul_f32_e32 v18, 0x3c800000, v18
	v_sin_f32_e32 v19, v18
	v_cos_f32_e32 v18, v18
	s_nop 0
	v_cndmask_b32_e32 v124, v19, v18, vcc
	v_add_u32_e32 v18, v5, v0
	v_and_b32_e32 v18, 63, v18
	v_cvt_f32_ubyte0_e32 v18, v18
	v_mul_f32_e32 v18, 0x3c800000, v18
	v_sin_f32_e32 v19, v18
	v_cos_f32_e32 v18, v18
	s_nop 0
	v_cndmask_b32_e32 v125, v19, v18, vcc
	v_add_u32_e32 v0, v0, v3
	s_waitcnt vmcnt(40)
	v_fmac_f32_e32 v17, v156, v118
	v_fmac_f32_e32 v17, v157, v119
	v_fmac_f32_e32 v17, v158, v120
	v_fmac_f32_e32 v17, v159, v121
	v_fmac_f32_e32 v17, v160, v122
	v_fmac_f32_e32 v17, v161, v123
	v_fmac_f32_e32 v17, v162, v124
	v_fmac_f32_e32 v17, v163, v125
	v_and_b32_e32 v18, 56, v0
	v_cvt_f32_ubyte0_e32 v18, v18
	v_mul_f32_e32 v18, 0x3c800000, v18
	v_sin_f32_e32 v19, v18
	v_cos_f32_e32 v18, v18
	s_nop 0
	v_cndmask_b32_e32 v118, v19, v18, vcc
	v_add_u32_e32 v18, v2, v0
	v_and_b32_e32 v18, 63, v18
	v_cvt_f32_ubyte0_e32 v18, v18
	v_mul_f32_e32 v18, 0x3c800000, v18
	v_sin_f32_e32 v19, v18
	v_cos_f32_e32 v18, v18
	s_nop 0
	v_cndmask_b32_e32 v119, v19, v18, vcc
	v_add_u32_e32 v18, v16, v0
	v_and_b32_e32 v18, 62, v18
	v_cvt_f32_ubyte0_e32 v18, v18
	v_mul_f32_e32 v18, 0x3c800000, v18
	v_sin_f32_e32 v19, v18
	v_cos_f32_e32 v18, v18
	s_nop 0
	v_cndmask_b32_e32 v120, v19, v18, vcc
	v_add_u32_e32 v18, v15, v0
	v_and_b32_e32 v18, 63, v18
	v_cvt_f32_ubyte0_e32 v18, v18
	v_mul_f32_e32 v18, 0x3c800000, v18
	v_sin_f32_e32 v19, v18
	v_cos_f32_e32 v18, v18
	s_nop 0
	v_cndmask_b32_e32 v121, v19, v18, vcc
	v_add_u32_e32 v18, v14, v0
	v_and_b32_e32 v18, 60, v18
	v_cvt_f32_ubyte0_e32 v18, v18
	v_mul_f32_e32 v18, 0x3c800000, v18
	v_sin_f32_e32 v19, v18
	v_cos_f32_e32 v18, v18
	s_nop 0
	v_cndmask_b32_e32 v122, v19, v18, vcc
	v_add_u32_e32 v18, v13, v0
	v_and_b32_e32 v18, 63, v18
	v_cvt_f32_ubyte0_e32 v18, v18
	v_mul_f32_e32 v18, 0x3c800000, v18
	v_sin_f32_e32 v19, v18
	v_cos_f32_e32 v18, v18
	s_nop 0
	v_cndmask_b32_e32 v123, v19, v18, vcc
	v_add_u32_e32 v18, v12, v0
	v_and_b32_e32 v18, 62, v18
	v_cvt_f32_ubyte0_e32 v18, v18
	v_mul_f32_e32 v18, 0x3c800000, v18
	v_sin_f32_e32 v19, v18
	v_cos_f32_e32 v18, v18
	s_nop 0
	v_cndmask_b32_e32 v124, v19, v18, vcc
	v_add_u32_e32 v18, v5, v0
	v_and_b32_e32 v18, 63, v18
	v_cvt_f32_ubyte0_e32 v18, v18
	v_mul_f32_e32 v18, 0x3c800000, v18
	v_sin_f32_e32 v19, v18
	v_cos_f32_e32 v18, v18
	s_nop 0
	v_cndmask_b32_e32 v125, v19, v18, vcc
	v_add_u32_e32 v0, v0, v3
	s_waitcnt vmcnt(32)
	v_fmac_f32_e32 v17, v164, v118
	v_fmac_f32_e32 v17, v165, v119
	v_fmac_f32_e32 v17, v166, v120
	v_fmac_f32_e32 v17, v167, v121
	v_fmac_f32_e32 v17, v168, v122
	v_fmac_f32_e32 v17, v169, v123
	v_fmac_f32_e32 v17, v170, v124
	v_fmac_f32_e32 v17, v171, v125
	v_and_b32_e32 v18, 56, v0
	v_cvt_f32_ubyte0_e32 v18, v18
	v_mul_f32_e32 v18, 0x3c800000, v18
	v_sin_f32_e32 v19, v18
	v_cos_f32_e32 v18, v18
	s_nop 0
	v_cndmask_b32_e32 v118, v19, v18, vcc
	v_add_u32_e32 v18, v2, v0
	v_and_b32_e32 v18, 63, v18
	v_cvt_f32_ubyte0_e32 v18, v18
	v_mul_f32_e32 v18, 0x3c800000, v18
	v_sin_f32_e32 v19, v18
	v_cos_f32_e32 v18, v18
	s_nop 0
	v_cndmask_b32_e32 v119, v19, v18, vcc
	v_add_u32_e32 v18, v16, v0
	v_and_b32_e32 v18, 62, v18
	v_cvt_f32_ubyte0_e32 v18, v18
	v_mul_f32_e32 v18, 0x3c800000, v18
	v_sin_f32_e32 v19, v18
	v_cos_f32_e32 v18, v18
	s_nop 0
	v_cndmask_b32_e32 v120, v19, v18, vcc
	v_add_u32_e32 v18, v15, v0
	v_and_b32_e32 v18, 63, v18
	v_cvt_f32_ubyte0_e32 v18, v18
	v_mul_f32_e32 v18, 0x3c800000, v18
	v_sin_f32_e32 v19, v18
	v_cos_f32_e32 v18, v18
	s_nop 0
	v_cndmask_b32_e32 v121, v19, v18, vcc
	v_add_u32_e32 v18, v14, v0
	v_and_b32_e32 v18, 60, v18
	v_cvt_f32_ubyte0_e32 v18, v18
	v_mul_f32_e32 v18, 0x3c800000, v18
	v_sin_f32_e32 v19, v18
	v_cos_f32_e32 v18, v18
	s_nop 0
	v_cndmask_b32_e32 v122, v19, v18, vcc
	v_add_u32_e32 v18, v13, v0
	v_and_b32_e32 v18, 63, v18
	v_cvt_f32_ubyte0_e32 v18, v18
	v_mul_f32_e32 v18, 0x3c800000, v18
	v_sin_f32_e32 v19, v18
	v_cos_f32_e32 v18, v18
	s_nop 0
	v_cndmask_b32_e32 v123, v19, v18, vcc
	v_add_u32_e32 v18, v12, v0
	v_and_b32_e32 v18, 62, v18
	v_cvt_f32_ubyte0_e32 v18, v18
	v_mul_f32_e32 v18, 0x3c800000, v18
	v_sin_f32_e32 v19, v18
	v_cos_f32_e32 v18, v18
	s_nop 0
	v_cndmask_b32_e32 v124, v19, v18, vcc
	v_add_u32_e32 v18, v5, v0
	v_and_b32_e32 v18, 63, v18
	v_cvt_f32_ubyte0_e32 v18, v18
	v_mul_f32_e32 v18, 0x3c800000, v18
	v_sin_f32_e32 v19, v18
	v_cos_f32_e32 v18, v18
	s_nop 0
	v_cndmask_b32_e32 v125, v19, v18, vcc
	v_add_u32_e32 v0, v0, v3
	s_waitcnt vmcnt(24)
	v_fmac_f32_e32 v17, v172, v118
	v_fmac_f32_e32 v17, v173, v119
	v_fmac_f32_e32 v17, v174, v120
	v_fmac_f32_e32 v17, v175, v121
	v_fmac_f32_e32 v17, v176, v122
	v_fmac_f32_e32 v17, v177, v123
	v_fmac_f32_e32 v17, v178, v124
	v_fmac_f32_e32 v17, v179, v125
	v_and_b32_e32 v18, 56, v0
	v_cvt_f32_ubyte0_e32 v18, v18
	v_mul_f32_e32 v18, 0x3c800000, v18
	v_sin_f32_e32 v19, v18
	v_cos_f32_e32 v18, v18
	s_nop 0
	v_cndmask_b32_e32 v118, v19, v18, vcc
	v_add_u32_e32 v18, v2, v0
	v_and_b32_e32 v18, 63, v18
	v_cvt_f32_ubyte0_e32 v18, v18
	v_mul_f32_e32 v18, 0x3c800000, v18
	v_sin_f32_e32 v19, v18
	v_cos_f32_e32 v18, v18
	s_nop 0
	v_cndmask_b32_e32 v119, v19, v18, vcc
	v_add_u32_e32 v18, v16, v0
	v_and_b32_e32 v18, 62, v18
	v_cvt_f32_ubyte0_e32 v18, v18
	v_mul_f32_e32 v18, 0x3c800000, v18
	v_sin_f32_e32 v19, v18
	v_cos_f32_e32 v18, v18
	s_nop 0
	v_cndmask_b32_e32 v120, v19, v18, vcc
	v_add_u32_e32 v18, v15, v0
	v_and_b32_e32 v18, 63, v18
	v_cvt_f32_ubyte0_e32 v18, v18
	v_mul_f32_e32 v18, 0x3c800000, v18
	v_sin_f32_e32 v19, v18
	v_cos_f32_e32 v18, v18
	s_nop 0
	v_cndmask_b32_e32 v121, v19, v18, vcc
	v_add_u32_e32 v18, v14, v0
	v_and_b32_e32 v18, 60, v18
	v_cvt_f32_ubyte0_e32 v18, v18
	v_mul_f32_e32 v18, 0x3c800000, v18
	v_sin_f32_e32 v19, v18
	v_cos_f32_e32 v18, v18
	s_nop 0
	v_cndmask_b32_e32 v122, v19, v18, vcc
	v_add_u32_e32 v18, v13, v0
	v_and_b32_e32 v18, 63, v18
	v_cvt_f32_ubyte0_e32 v18, v18
	v_mul_f32_e32 v18, 0x3c800000, v18
	v_sin_f32_e32 v19, v18
	v_cos_f32_e32 v18, v18
	s_nop 0
	v_cndmask_b32_e32 v123, v19, v18, vcc
	v_add_u32_e32 v18, v12, v0
	v_and_b32_e32 v18, 62, v18
	v_cvt_f32_ubyte0_e32 v18, v18
	v_mul_f32_e32 v18, 0x3c800000, v18
	v_sin_f32_e32 v19, v18
	v_cos_f32_e32 v18, v18
	s_nop 0
	v_cndmask_b32_e32 v124, v19, v18, vcc
	v_add_u32_e32 v18, v5, v0
	v_and_b32_e32 v18, 63, v18
	v_cvt_f32_ubyte0_e32 v18, v18
	v_mul_f32_e32 v18, 0x3c800000, v18
	v_sin_f32_e32 v19, v18
	v_cos_f32_e32 v18, v18
	s_nop 0
	v_cndmask_b32_e32 v125, v19, v18, vcc
	v_add_u32_e32 v0, v0, v3
	s_waitcnt vmcnt(16)
	v_fmac_f32_e32 v17, v180, v118
	v_fmac_f32_e32 v17, v181, v119
	v_fmac_f32_e32 v17, v182, v120
	v_fmac_f32_e32 v17, v183, v121
	v_fmac_f32_e32 v17, v184, v122
	v_fmac_f32_e32 v17, v185, v123
	v_fmac_f32_e32 v17, v186, v124
	v_fmac_f32_e32 v17, v187, v125
	v_and_b32_e32 v18, 56, v0
	v_cvt_f32_ubyte0_e32 v18, v18
	v_mul_f32_e32 v18, 0x3c800000, v18
	v_sin_f32_e32 v19, v18
	v_cos_f32_e32 v18, v18
	s_nop 0
	v_cndmask_b32_e32 v118, v19, v18, vcc
	v_add_u32_e32 v18, v2, v0
	v_and_b32_e32 v18, 63, v18
	v_cvt_f32_ubyte0_e32 v18, v18
	v_mul_f32_e32 v18, 0x3c800000, v18
	v_sin_f32_e32 v19, v18
	v_cos_f32_e32 v18, v18
	s_nop 0
	v_cndmask_b32_e32 v119, v19, v18, vcc
	v_add_u32_e32 v18, v16, v0
	v_and_b32_e32 v18, 62, v18
	v_cvt_f32_ubyte0_e32 v18, v18
	v_mul_f32_e32 v18, 0x3c800000, v18
	v_sin_f32_e32 v19, v18
	v_cos_f32_e32 v18, v18
	s_nop 0
	v_cndmask_b32_e32 v120, v19, v18, vcc
	v_add_u32_e32 v18, v15, v0
	v_and_b32_e32 v18, 63, v18
	v_cvt_f32_ubyte0_e32 v18, v18
	v_mul_f32_e32 v18, 0x3c800000, v18
	v_sin_f32_e32 v19, v18
	v_cos_f32_e32 v18, v18
	s_nop 0
	v_cndmask_b32_e32 v121, v19, v18, vcc
	v_add_u32_e32 v18, v14, v0
	v_and_b32_e32 v18, 60, v18
	v_cvt_f32_ubyte0_e32 v18, v18
	v_mul_f32_e32 v18, 0x3c800000, v18
	v_sin_f32_e32 v19, v18
	v_cos_f32_e32 v18, v18
	s_nop 0
	v_cndmask_b32_e32 v122, v19, v18, vcc
	v_add_u32_e32 v18, v13, v0
	v_and_b32_e32 v18, 63, v18
	v_cvt_f32_ubyte0_e32 v18, v18
	v_mul_f32_e32 v18, 0x3c800000, v18
	v_sin_f32_e32 v19, v18
	v_cos_f32_e32 v18, v18
	s_nop 0
	v_cndmask_b32_e32 v123, v19, v18, vcc
	v_add_u32_e32 v18, v12, v0
	v_and_b32_e32 v18, 62, v18
	v_cvt_f32_ubyte0_e32 v18, v18
	v_mul_f32_e32 v18, 0x3c800000, v18
	v_sin_f32_e32 v19, v18
	v_cos_f32_e32 v18, v18
	s_nop 0
	v_cndmask_b32_e32 v124, v19, v18, vcc
	v_add_u32_e32 v18, v5, v0
	v_and_b32_e32 v18, 63, v18
	v_cvt_f32_ubyte0_e32 v18, v18
	v_mul_f32_e32 v18, 0x3c800000, v18
	v_sin_f32_e32 v19, v18
	v_cos_f32_e32 v18, v18
	s_nop 0
	v_cndmask_b32_e32 v125, v19, v18, vcc
	v_add_u32_e32 v0, v0, v3
	s_waitcnt vmcnt(8)
	v_fmac_f32_e32 v17, v188, v118
	v_fmac_f32_e32 v17, v189, v119
	v_fmac_f32_e32 v17, v190, v120
	v_fmac_f32_e32 v17, v191, v121
	v_fmac_f32_e32 v17, v192, v122
	v_fmac_f32_e32 v17, v193, v123
	v_fmac_f32_e32 v17, v194, v124
	v_fmac_f32_e32 v17, v195, v125
	v_and_b32_e32 v18, 56, v0
	v_cvt_f32_ubyte0_e32 v18, v18
	v_mul_f32_e32 v18, 0x3c800000, v18
	v_sin_f32_e32 v19, v18
	v_cos_f32_e32 v18, v18
	s_nop 0
	v_cndmask_b32_e32 v118, v19, v18, vcc
	v_add_u32_e32 v18, v2, v0
	v_and_b32_e32 v18, 63, v18
	v_cvt_f32_ubyte0_e32 v18, v18
	v_mul_f32_e32 v18, 0x3c800000, v18
	v_sin_f32_e32 v19, v18
	v_cos_f32_e32 v18, v18
	s_nop 0
	v_cndmask_b32_e32 v119, v19, v18, vcc
	v_add_u32_e32 v18, v16, v0
	v_and_b32_e32 v18, 62, v18
	v_cvt_f32_ubyte0_e32 v18, v18
	v_mul_f32_e32 v18, 0x3c800000, v18
	v_sin_f32_e32 v19, v18
	v_cos_f32_e32 v18, v18
	s_nop 0
	v_cndmask_b32_e32 v120, v19, v18, vcc
	v_add_u32_e32 v18, v15, v0
	v_and_b32_e32 v18, 63, v18
	v_cvt_f32_ubyte0_e32 v18, v18
	v_mul_f32_e32 v18, 0x3c800000, v18
	v_sin_f32_e32 v19, v18
	v_cos_f32_e32 v18, v18
	s_nop 0
	v_cndmask_b32_e32 v121, v19, v18, vcc
	v_add_u32_e32 v18, v14, v0
	v_and_b32_e32 v18, 60, v18
	v_cvt_f32_ubyte0_e32 v18, v18
	v_mul_f32_e32 v18, 0x3c800000, v18
	v_sin_f32_e32 v19, v18
	v_cos_f32_e32 v18, v18
	s_nop 0
	v_cndmask_b32_e32 v122, v19, v18, vcc
	v_add_u32_e32 v18, v13, v0
	v_and_b32_e32 v18, 63, v18
	v_cvt_f32_ubyte0_e32 v18, v18
	v_mul_f32_e32 v18, 0x3c800000, v18
	v_sin_f32_e32 v19, v18
	v_cos_f32_e32 v18, v18
	s_nop 0
	v_cndmask_b32_e32 v123, v19, v18, vcc
	v_add_u32_e32 v18, v12, v0
	v_and_b32_e32 v18, 62, v18
	v_cvt_f32_ubyte0_e32 v18, v18
	v_mul_f32_e32 v18, 0x3c800000, v18
	v_sin_f32_e32 v19, v18
	v_cos_f32_e32 v18, v18
	s_nop 0
	v_cndmask_b32_e32 v124, v19, v18, vcc
	v_add_u32_e32 v18, v5, v0
	v_and_b32_e32 v18, 63, v18
	v_cvt_f32_ubyte0_e32 v18, v18
	v_mul_f32_e32 v18, 0x3c800000, v18
	v_sin_f32_e32 v19, v18
	v_cos_f32_e32 v18, v18
	s_nop 0
	v_cndmask_b32_e32 v125, v19, v18, vcc
	v_add_u32_e32 v0, v0, v3
	s_waitcnt vmcnt(0)
	v_fmac_f32_e32 v17, v196, v118
	v_fmac_f32_e32 v17, v197, v119
	v_fmac_f32_e32 v17, v198, v120
	v_fmac_f32_e32 v17, v199, v121
	v_fmac_f32_e32 v17, v200, v122
	v_fmac_f32_e32 v17, v201, v123
	v_fmac_f32_e32 v17, v202, v124
	v_fmac_f32_e32 v17, v203, v125
	v_mul_f32_e32 v0, 0x3e000000, v17
	v_ashrrev_i32_e32 v5, 31, v4
	v_cvt_pk_bf16_f32 v0, v0, s0
	v_lshl_add_u64 v[4:5], v[4:5], 1, s[58:59]
	global_store_short v[4:5], v0, off
